# DPP-style intra-wave movement: EpiRes epilogue row reductions via v_permlane16/32_swap instead of ds_bpermute LDS round trips
# speedup vs baseline: 1.0055x; 1.0055x over previous
;     __device__ __forceinline__ void publish(const f32x4 (&v)[2][2][4][2], const Unit& u, int wr, int wc, int fr, int fq, PG8_LAS unsigned char* lds, int wid, int lane) const {
;     ...
;                 float s = 0.f;
; #pragma unroll
;                 for (int bj = 0; bj < 2; ++bj)
; #pragma unroll
;                     for (int n = 0; n < 2; ++n) { const f32x4 x = v[ai][bj][m][n]; s += (x[0] * x[0] + x[1] * x[1]) + (x[2] * x[2] + x[3] * x[3]); }
;                 s += shx(s, 16); s += shx(s, 32);
;                 if (fq == 0) P[(ai * HALF + wr * 64 + m * 16 + fr) * 4 + wc] = s;
.LBB0_617:
	v_mul_f32_e32 v104, v141, v141
	v_mul_f32_e32 v105, v143, v143
	v_fmac_f32_e32 v104, v140, v140
	v_fmac_f32_e32 v105, v142, v142
	v_add_f32_e32 v104, v104, v105
	v_mul_f32_e32 v105, v137, v137
	v_mul_f32_e32 v106, v139, v139
	v_fmac_f32_e32 v105, v136, v136
	v_fmac_f32_e32 v106, v138, v138
	v_add_f32_e32 v105, v105, v106
	v_add_f32_e32 v104, v104, v105
	v_mul_f32_e32 v105, v129, v129
	v_mul_f32_e32 v106, v131, v131
	v_fmac_f32_e32 v105, v128, v128
	v_fmac_f32_e32 v106, v130, v130
	v_add_f32_e32 v105, v105, v106
	v_add_f32_e32 v104, v104, v105
	v_mul_f32_e32 v105, v121, v121
	v_mul_f32_e32 v106, v123, v123
	v_fmac_f32_e32 v105, v120, v120
	v_fmac_f32_e32 v106, v122, v122
	v_add_f32_e32 v105, v105, v106
	v_mbcnt_lo_u32_b32 v248, -1, 0
	v_mbcnt_hi_u32_b32 v248, -1, v248
	v_add_f32_e32 v104, v104, v105
	v_mbcnt_lo_u32_b32 v105, -1, 0
	v_mbcnt_hi_u32_b32 v105, -1, v105
	v_cmp_gt_u32_e64 s[6:7], 16, v248
	v_lshlrev_b32_e32 v105, 2, v105
	v_xor_b32_e32 v105, 64, v105
	v_mov_b32_e32 v105, v104
	s_nop 1
	v_permlane16_swap_b32_e32 v104, v105
	s_waitcnt lgkmcnt(0)
	v_add_f32_e32 v105, v104, v105
	v_mbcnt_lo_u32_b32 v104, -1, 0
	v_mbcnt_hi_u32_b32 v104, -1, v104
	s_nop 0
	v_lshlrev_b32_e32 v104, 2, v104
	v_xor_b32_e32 v104, 0x80, v104
	v_mov_b32_e32 v106, v105
	s_nop 1
	v_permlane32_swap_b32_e32 v105, v106
	v_lshl_add_u32 v104, v248, 4, s83
	s_and_saveexec_b64 s[8:9], s[6:7]
	s_cbranch_execz .LBB0_619
	s_waitcnt lgkmcnt(0)
	v_add_f32_e32 v105, v105, v106
	ds_write_b32 v104, v105
.LBB0_619:
	s_or_b64 exec, exec, s[8:9]
	v_mul_f32_e32 v105, v117, v117
	s_waitcnt lgkmcnt(0)
	v_mul_f32_e32 v106, v119, v119
	v_fmac_f32_e32 v105, v116, v116
	v_fmac_f32_e32 v106, v118, v118
	v_add_f32_e32 v105, v105, v106
	v_mul_f32_e32 v106, v109, v109
	v_mul_f32_e32 v107, v111, v111
	v_fmac_f32_e32 v106, v108, v108
	v_fmac_f32_e32 v107, v110, v110
	v_add_f32_e32 v106, v106, v107
	v_add_f32_e32 v105, v105, v106
	v_mul_f32_e32 v106, v101, v101
	v_mul_f32_e32 v107, v103, v103
	v_fmac_f32_e32 v106, v100, v100
	v_fmac_f32_e32 v107, v102, v102
	v_add_f32_e32 v106, v106, v107
	v_add_f32_e32 v105, v105, v106
	v_mul_f32_e32 v106, v97, v97
	v_mul_f32_e32 v107, v99, v99
	v_fmac_f32_e32 v106, v96, v96
	v_fmac_f32_e32 v107, v98, v98
	v_add_f32_e32 v106, v106, v107
	v_add_f32_e32 v105, v105, v106
	v_mbcnt_lo_u32_b32 v106, -1, 0
	v_mbcnt_hi_u32_b32 v106, -1, v106
	s_nop 0
	v_lshlrev_b32_e32 v106, 2, v106
	v_xor_b32_e32 v106, 64, v106
	v_mov_b32_e32 v106, v105
	s_nop 1
	v_permlane16_swap_b32_e32 v105, v106
	s_waitcnt lgkmcnt(0)
	v_add_f32_e32 v105, v105, v106
	v_mbcnt_lo_u32_b32 v106, -1, 0
	v_mbcnt_hi_u32_b32 v106, -1, v106
	s_nop 0
	v_lshlrev_b32_e32 v106, 2, v106
	v_xor_b32_e32 v106, 0x80, v106
	v_mov_b32_e32 v106, v105
	s_nop 1
	v_permlane32_swap_b32_e32 v105, v106
	s_and_saveexec_b64 s[8:9], s[6:7]
	s_cbranch_execz .LBB0_621
	s_waitcnt lgkmcnt(0)
	v_add_f32_e32 v105, v105, v106
	ds_write_b32 v104, v105 offset:256
.LBB0_621:
	s_or_b64 exec, exec, s[8:9]
	v_mul_f32_e32 v105, v93, v93
	s_waitcnt lgkmcnt(0)
	v_mul_f32_e32 v106, v95, v95
	v_fmac_f32_e32 v105, v92, v92
	v_fmac_f32_e32 v106, v94, v94
	v_add_f32_e32 v105, v105, v106
	v_mul_f32_e32 v106, v89, v89
	v_mul_f32_e32 v107, v91, v91
	v_fmac_f32_e32 v106, v88, v88
	v_fmac_f32_e32 v107, v90, v90
	v_add_f32_e32 v106, v106, v107
	v_add_f32_e32 v105, v105, v106
	v_mul_f32_e32 v106, v85, v85
	v_mul_f32_e32 v107, v87, v87
	v_fmac_f32_e32 v106, v84, v84
	v_fmac_f32_e32 v107, v86, v86
	v_add_f32_e32 v106, v106, v107
	v_add_f32_e32 v105, v105, v106
	v_mul_f32_e32 v106, v81, v81
	v_mul_f32_e32 v107, v83, v83
	v_fmac_f32_e32 v106, v80, v80
	v_fmac_f32_e32 v107, v82, v82
	v_add_f32_e32 v106, v106, v107
	v_add_f32_e32 v105, v105, v106
	v_mbcnt_lo_u32_b32 v106, -1, 0
	v_mbcnt_hi_u32_b32 v106, -1, v106
	s_nop 0
	v_lshlrev_b32_e32 v106, 2, v106
	v_xor_b32_e32 v106, 64, v106
	v_mov_b32_e32 v106, v105
	s_nop 1
	v_permlane16_swap_b32_e32 v105, v106
	s_waitcnt lgkmcnt(0)
	v_add_f32_e32 v105, v105, v106
	v_mbcnt_lo_u32_b32 v106, -1, 0
	v_mbcnt_hi_u32_b32 v106, -1, v106
	s_nop 0
	v_lshlrev_b32_e32 v106, 2, v106
	v_xor_b32_e32 v106, 0x80, v106
	v_mov_b32_e32 v106, v105
	s_nop 1
	v_permlane32_swap_b32_e32 v105, v106
	s_and_saveexec_b64 s[8:9], s[6:7]
	s_cbranch_execz .LBB0_623
	s_waitcnt lgkmcnt(0)
	v_add_f32_e32 v105, v105, v106
	ds_write_b32 v104, v105 offset:512
.LBB0_623:
	s_or_b64 exec, exec, s[8:9]
	v_mul_f32_e32 v105, v77, v77
	s_waitcnt lgkmcnt(0)
	v_mul_f32_e32 v106, v79, v79
	v_fmac_f32_e32 v105, v76, v76
	v_fmac_f32_e32 v106, v78, v78
	v_add_f32_e32 v105, v105, v106
	v_mul_f32_e32 v106, v73, v73
	v_mul_f32_e32 v107, v75, v75
	v_fmac_f32_e32 v106, v72, v72
	v_fmac_f32_e32 v107, v74, v74
	v_add_f32_e32 v106, v106, v107
	v_add_f32_e32 v105, v105, v106
	v_mul_f32_e32 v106, v69, v69
	v_mul_f32_e32 v107, v71, v71
	v_fmac_f32_e32 v106, v68, v68
	v_fmac_f32_e32 v107, v70, v70
	v_add_f32_e32 v106, v106, v107
	v_add_f32_e32 v105, v105, v106
	v_mul_f32_e32 v106, v65, v65
	v_mul_f32_e32 v107, v67, v67
	v_fmac_f32_e32 v106, v64, v64
	v_fmac_f32_e32 v107, v66, v66
	v_add_f32_e32 v106, v106, v107
	v_add_f32_e32 v105, v105, v106
	v_mbcnt_lo_u32_b32 v106, -1, 0
	v_mbcnt_hi_u32_b32 v106, -1, v106
	s_nop 0
	v_lshlrev_b32_e32 v106, 2, v106
	v_xor_b32_e32 v106, 64, v106
	v_mov_b32_e32 v106, v105
	s_nop 1
	v_permlane16_swap_b32_e32 v105, v106
	s_waitcnt lgkmcnt(0)
	v_add_f32_e32 v105, v105, v106
	v_mbcnt_lo_u32_b32 v106, -1, 0
	v_mbcnt_hi_u32_b32 v106, -1, v106
	s_nop 0
	v_lshlrev_b32_e32 v106, 2, v106
	v_xor_b32_e32 v106, 0x80, v106
	v_mov_b32_e32 v106, v105
	s_nop 1
	v_permlane32_swap_b32_e32 v105, v106
	s_and_saveexec_b64 s[8:9], s[6:7]
	s_cbranch_execz .LBB0_625
	s_waitcnt lgkmcnt(0)
	v_add_f32_e32 v105, v105, v106
	ds_write_b32 v104, v105 offset:768
;     __device__ __forceinline__ void publish(const f32x4 (&v)[2][2][4][2], const Unit& u, int wr, int wc, int fr, int fq, PG8_LAS unsigned char* lds, int wid, int lane) const {
;     ...
;                 float s = 0.f;
; #pragma unroll
;                 for (int bj = 0; bj < 2; ++bj)
; #pragma unroll
;                     for (int n = 0; n < 2; ++n) { const f32x4 x = v[ai][bj][m][n]; s += (x[0] * x[0] + x[1] * x[1]) + (x[2] * x[2] + x[3] * x[3]); }
;                 s += shx(s, 16); s += shx(s, 32);
;                 if (fq == 0) P[(ai * HALF + wr * 64 + m * 16 + fr) * 4 + wc] = s;
.LBB0_625:
	s_or_b64 exec, exec, s[8:9]
	v_mul_f32_e32 v105, v61, v61
	s_waitcnt lgkmcnt(0)
	v_mul_f32_e32 v106, v63, v63
	v_fmac_f32_e32 v105, v60, v60
	v_fmac_f32_e32 v106, v62, v62
	v_add_f32_e32 v105, v105, v106
	v_mul_f32_e32 v106, v57, v57
	v_mul_f32_e32 v107, v59, v59
	v_fmac_f32_e32 v106, v56, v56
	v_fmac_f32_e32 v107, v58, v58
	v_add_f32_e32 v106, v106, v107
	v_add_f32_e32 v105, v105, v106
	v_mul_f32_e32 v106, v53, v53
	v_mul_f32_e32 v107, v55, v55
	v_fmac_f32_e32 v106, v52, v52
	v_fmac_f32_e32 v107, v54, v54
	v_add_f32_e32 v106, v106, v107
	v_add_f32_e32 v105, v105, v106
	v_mul_f32_e32 v106, v49, v49
	v_mul_f32_e32 v107, v51, v51
	v_fmac_f32_e32 v106, v48, v48
	v_fmac_f32_e32 v107, v50, v50
	v_add_f32_e32 v106, v106, v107
	v_add_f32_e32 v105, v105, v106
	v_mbcnt_lo_u32_b32 v106, -1, 0
	v_mbcnt_hi_u32_b32 v106, -1, v106
	s_nop 0
	v_lshlrev_b32_e32 v106, 2, v106
	v_xor_b32_e32 v106, 64, v106
	v_mov_b32_e32 v106, v105
	s_nop 1
	v_permlane16_swap_b32_e32 v105, v106
	s_waitcnt lgkmcnt(0)
	v_add_f32_e32 v105, v105, v106
	v_mbcnt_lo_u32_b32 v106, -1, 0
	v_mbcnt_hi_u32_b32 v106, -1, v106
	s_nop 0
	v_lshlrev_b32_e32 v106, 2, v106
	v_xor_b32_e32 v106, 0x80, v106
	v_mov_b32_e32 v106, v105
	s_nop 1
	v_permlane32_swap_b32_e32 v105, v106
	s_and_saveexec_b64 s[8:9], s[6:7]
	s_cbranch_execz .LBB0_627
	s_waitcnt lgkmcnt(0)
	v_add_f32_e32 v105, v105, v106
	ds_write_b32 v104, v105 offset:2048
.LBB0_627:
	s_or_b64 exec, exec, s[8:9]
	v_mul_f32_e32 v105, v45, v45
	s_waitcnt lgkmcnt(0)
	v_mul_f32_e32 v106, v47, v47
	v_fmac_f32_e32 v105, v44, v44
	v_fmac_f32_e32 v106, v46, v46
	v_add_f32_e32 v105, v105, v106
	v_mul_f32_e32 v106, v41, v41
	v_mul_f32_e32 v107, v43, v43
	v_fmac_f32_e32 v106, v40, v40
	v_fmac_f32_e32 v107, v42, v42
	v_add_f32_e32 v106, v106, v107
	v_add_f32_e32 v105, v105, v106
	v_mul_f32_e32 v106, v37, v37
	v_mul_f32_e32 v107, v39, v39
	v_fmac_f32_e32 v106, v36, v36
	v_fmac_f32_e32 v107, v38, v38
	v_add_f32_e32 v106, v106, v107
	v_add_f32_e32 v105, v105, v106
	v_mul_f32_e32 v106, v33, v33
	v_mul_f32_e32 v107, v35, v35
	v_fmac_f32_e32 v106, v32, v32
	v_fmac_f32_e32 v107, v34, v34
	v_add_f32_e32 v106, v106, v107
	v_add_f32_e32 v105, v105, v106
	v_mbcnt_lo_u32_b32 v106, -1, 0
	v_mbcnt_hi_u32_b32 v106, -1, v106
	s_nop 0
	v_lshlrev_b32_e32 v106, 2, v106
	v_xor_b32_e32 v106, 64, v106
	v_mov_b32_e32 v106, v105
	s_nop 1
	v_permlane16_swap_b32_e32 v105, v106
	s_waitcnt lgkmcnt(0)
	v_add_f32_e32 v105, v105, v106
	v_mbcnt_lo_u32_b32 v106, -1, 0
	v_mbcnt_hi_u32_b32 v106, -1, v106
	s_nop 0
	v_lshlrev_b32_e32 v106, 2, v106
	v_xor_b32_e32 v106, 0x80, v106
	v_mov_b32_e32 v106, v105
	s_nop 1
	v_permlane32_swap_b32_e32 v105, v106
	s_and_saveexec_b64 s[8:9], s[6:7]
	s_cbranch_execz .LBB0_629
	s_waitcnt lgkmcnt(0)
	v_add_f32_e32 v105, v105, v106
	ds_write_b32 v104, v105 offset:2304
.LBB0_629:
	s_or_b64 exec, exec, s[8:9]
	v_mul_f32_e32 v105, v29, v29
	s_waitcnt lgkmcnt(0)
	v_mul_f32_e32 v106, v31, v31
	v_fmac_f32_e32 v105, v28, v28
	v_fmac_f32_e32 v106, v30, v30
	v_add_f32_e32 v105, v105, v106
	v_mul_f32_e32 v106, v25, v25
	v_mul_f32_e32 v107, v27, v27
	v_fmac_f32_e32 v106, v24, v24
	v_fmac_f32_e32 v107, v26, v26
	v_add_f32_e32 v106, v106, v107
	v_add_f32_e32 v105, v105, v106
	v_mul_f32_e32 v106, v21, v21
	v_mul_f32_e32 v107, v23, v23
	v_fmac_f32_e32 v106, v20, v20
	v_fmac_f32_e32 v107, v22, v22
	v_add_f32_e32 v106, v106, v107
	v_add_f32_e32 v105, v105, v106
	v_mul_f32_e32 v106, v17, v17
	v_mul_f32_e32 v107, v19, v19
	v_fmac_f32_e32 v106, v16, v16
	v_fmac_f32_e32 v107, v18, v18
	v_add_f32_e32 v106, v106, v107
	v_add_f32_e32 v105, v105, v106
	v_mbcnt_lo_u32_b32 v106, -1, 0
	v_mbcnt_hi_u32_b32 v106, -1, v106
	s_nop 0
	v_lshlrev_b32_e32 v106, 2, v106
	v_xor_b32_e32 v106, 64, v106
	v_mov_b32_e32 v106, v105
	s_nop 1
	v_permlane16_swap_b32_e32 v105, v106
	s_waitcnt lgkmcnt(0)
	v_add_f32_e32 v105, v105, v106
	v_mbcnt_lo_u32_b32 v106, -1, 0
	v_mbcnt_hi_u32_b32 v106, -1, v106
	s_nop 0
	v_lshlrev_b32_e32 v106, 2, v106
	v_xor_b32_e32 v106, 0x80, v106
	v_mov_b32_e32 v106, v105
	s_nop 1
	v_permlane32_swap_b32_e32 v105, v106
	s_and_saveexec_b64 s[8:9], s[6:7]
	s_cbranch_execz .LBB0_631
	s_waitcnt lgkmcnt(0)
	v_add_f32_e32 v105, v105, v106
	ds_write_b32 v104, v105 offset:2560
.LBB0_631:
	s_or_b64 exec, exec, s[8:9]
	v_mul_f32_e32 v105, v13, v13
	s_waitcnt lgkmcnt(0)
	v_mul_f32_e32 v106, v15, v15
	v_fmac_f32_e32 v105, v12, v12
	v_fmac_f32_e32 v106, v14, v14
	v_add_f32_e32 v105, v105, v106
	v_mul_f32_e32 v106, v9, v9
	v_mul_f32_e32 v107, v11, v11
	v_fmac_f32_e32 v106, v8, v8
	v_fmac_f32_e32 v107, v10, v10
	v_add_f32_e32 v106, v106, v107
	v_add_f32_e32 v105, v105, v106
	v_mul_f32_e32 v106, v5, v5
	v_mul_f32_e32 v107, v7, v7
	v_fmac_f32_e32 v106, v4, v4
	v_fmac_f32_e32 v107, v6, v6
	v_add_f32_e32 v106, v106, v107
	v_add_f32_e32 v105, v105, v106
	v_mul_f32_e32 v106, v1, v1
	v_mul_f32_e32 v107, v3, v3
	v_fmac_f32_e32 v106, v0, v0
	v_fmac_f32_e32 v107, v2, v2
	v_add_f32_e32 v106, v106, v107
	v_add_f32_e32 v105, v105, v106
	v_mbcnt_lo_u32_b32 v106, -1, 0
	v_mbcnt_hi_u32_b32 v106, -1, v106
	s_nop 0
	v_lshlrev_b32_e32 v106, 2, v106
	v_xor_b32_e32 v106, 64, v106
	v_mov_b32_e32 v106, v105
	s_nop 1
	v_permlane16_swap_b32_e32 v105, v106
	s_waitcnt lgkmcnt(0)
	v_add_f32_e32 v105, v105, v106
	v_mbcnt_lo_u32_b32 v106, -1, 0
	v_mbcnt_hi_u32_b32 v106, -1, v106
	s_nop 0
	v_lshlrev_b32_e32 v106, 2, v106
	v_xor_b32_e32 v106, 0x80, v106
	v_mov_b32_e32 v106, v105
	s_nop 1
	v_permlane32_swap_b32_e32 v105, v106
	s_and_saveexec_b64 s[8:9], s[6:7]
	s_cbranch_execz .LBB0_633
	s_waitcnt lgkmcnt(0)
	v_add_f32_e32 v105, v105, v106
	ds_write_b32 v104, v105 offset:2816

;     __device__ __forceinline__ void operator()(f32x4 (&acc)[2][2][4][2], const Unit& u, int wr, int wc, int fr_, int fq_) const {
;     ...
;                     for (int n = 0; n < 2; ++n) { x1[n] = xo[n] + gv[bj][n] * acc[ai][bj][m][n] * nh;
;                         s2 += (x1[n][0] * x1[n][0] + x1[n][1] * x1[n][1]) + (x1[n][2] * x1[n][2] + x1[n][3] * x1[n][3]); }
;                     if (!last) store8(xb + off + bj * HALF, x1[0], x1[1]);
;                     else { *(f32x4*)(xout + off + bj * HALF) = x1[0]; *(f32x4*)(xout + off + bj * HALF + 4) = x1[1]; } }
;                 if (!last) { s2 += shx(s2, 16); s2 += shx(s2, 32); if (fq == 0) P[r * 4 + wc] = s2; }
.LBB0_658:
	v_mul_f32_e32 v141, v141, v141
	v_mul_f32_e32 v137, v137, v137
	v_fmac_f32_e32 v141, v140, v140
	v_mul_f32_e32 v140, v143, v143
	v_fmac_f32_e32 v137, v136, v136
	v_mul_f32_e32 v136, v139, v139
	v_mul_f32_e32 v129, v129, v129
	v_mul_f32_e32 v121, v121, v121
	v_fmac_f32_e32 v140, v142, v142
	v_fmac_f32_e32 v136, v138, v138
	v_fmac_f32_e32 v129, v128, v128
	v_mul_f32_e32 v128, v131, v131
	v_fmac_f32_e32 v121, v120, v120
	v_mul_f32_e32 v120, v123, v123
	v_add_f32_e32 v140, v141, v140
	v_add_f32_e32 v136, v137, v136
	v_fmac_f32_e32 v128, v130, v130
	v_fmac_f32_e32 v120, v122, v122
	v_add_f32_e32 v136, v140, v136
	v_add_f32_e32 v128, v129, v128
	v_add_f32_e32 v120, v121, v120
	v_mbcnt_lo_u32_b32 v121, -1, 0
	v_mbcnt_hi_u32_b32 v121, -1, v121
	v_add_f32_e32 v128, v128, v136
	v_lshlrev_b32_e32 v121, 2, v121
	v_add_f32_e32 v120, v120, v128
	v_xor_b32_e32 v121, 64, v121
	v_mov_b32_e32 v121, v120
	s_nop 1
	v_permlane16_swap_b32_e32 v120, v121
	s_waitcnt lgkmcnt(0)
	v_add_f32_e32 v120, v120, v121
	v_mbcnt_lo_u32_b32 v121, -1, 0
	v_mbcnt_hi_u32_b32 v121, -1, v121
	s_nop 0
	v_lshlrev_b32_e32 v121, 2, v121
	v_xor_b32_e32 v121, 0x80, v121
	v_mov_b32_e32 v121, v120
	s_nop 1
	v_permlane32_swap_b32_e32 v120, v121
	s_and_saveexec_b64 s[38:39], s[6:7]
	s_cbranch_execz .LBB0_660
	v_lshl_add_u32 v122, v249, 4, s82
	s_waitcnt lgkmcnt(0)
	v_add_f32_e32 v120, v120, v121
	ds_write_b32 v122, v120

;     __device__ __forceinline__ void operator()(f32x4 (&acc)[2][2][4][2], const Unit& u, int wr, int wc, int fr_, int fq_) const {
;     ...
;                     for (int n = 0; n < 2; ++n) { x1[n] = xo[n] + gv[bj][n] * acc[ai][bj][m][n] * nh;
;                         s2 += (x1[n][0] * x1[n][0] + x1[n][1] * x1[n][1]) + (x1[n][2] * x1[n][2] + x1[n][3] * x1[n][3]); }
;                     if (!last) store8(xb + off + bj * HALF, x1[0], x1[1]);
;                     else { *(f32x4*)(xout + off + bj * HALF) = x1[0]; *(f32x4*)(xout + off + bj * HALF + 4) = x1[1]; } }
;                 if (!last) { s2 += shx(s2, 16); s2 += shx(s2, 32); if (fq == 0) P[r * 4 + wc] = s2; }
.LBB0_670:
	v_mul_f32_e32 v117, v117, v117
	v_mul_f32_e32 v109, v109, v109
	v_fmac_f32_e32 v117, v116, v116
	v_mul_f32_e32 v116, v119, v119
	v_fmac_f32_e32 v109, v108, v108
	v_mul_f32_e32 v108, v111, v111
	v_mul_f32_e32 v101, v101, v101
	v_mul_f32_e32 v97, v97, v97
	v_fmac_f32_e32 v116, v118, v118
	v_fmac_f32_e32 v108, v110, v110
	v_fmac_f32_e32 v101, v100, v100
	v_mul_f32_e32 v100, v103, v103
	v_fmac_f32_e32 v97, v96, v96
	v_mul_f32_e32 v96, v99, v99
	v_add_f32_e32 v116, v117, v116
	v_add_f32_e32 v108, v109, v108
	v_fmac_f32_e32 v100, v102, v102
	v_fmac_f32_e32 v96, v98, v98
	v_add_f32_e32 v108, v116, v108
	v_add_f32_e32 v100, v101, v100
	v_add_f32_e32 v96, v97, v96
	v_mbcnt_lo_u32_b32 v97, -1, 0
	v_mbcnt_hi_u32_b32 v97, -1, v97
	v_add_f32_e32 v100, v100, v108
	v_lshlrev_b32_e32 v97, 2, v97
	v_add_f32_e32 v96, v96, v100
	v_xor_b32_e32 v97, 64, v97
	v_mov_b32_e32 v97, v96
	s_nop 1
	v_permlane16_swap_b32_e32 v96, v97
	s_waitcnt lgkmcnt(0)
	v_add_f32_e32 v96, v96, v97
	v_mbcnt_lo_u32_b32 v97, -1, 0
	v_mbcnt_hi_u32_b32 v97, -1, v97
	s_nop 0
	v_lshlrev_b32_e32 v97, 2, v97
	v_xor_b32_e32 v97, 0x80, v97
	v_mov_b32_e32 v97, v96
	s_nop 1
	v_permlane32_swap_b32_e32 v96, v97
	s_and_saveexec_b64 s[38:39], s[6:7]
	s_cbranch_execz .LBB0_672
	v_lshl_add_u32 v98, v130, 4, s82
	s_waitcnt lgkmcnt(0)
	v_add_f32_e32 v96, v96, v97
	ds_write_b32 v98, v96

;     __device__ __forceinline__ void operator()(f32x4 (&acc)[2][2][4][2], const Unit& u, int wr, int wc, int fr_, int fq_) const {
;     ...
;                     for (int n = 0; n < 2; ++n) { x1[n] = xo[n] + gv[bj][n] * acc[ai][bj][m][n] * nh;
;                         s2 += (x1[n][0] * x1[n][0] + x1[n][1] * x1[n][1]) + (x1[n][2] * x1[n][2] + x1[n][3] * x1[n][3]); }
;                     if (!last) store8(xb + off + bj * HALF, x1[0], x1[1]);
;                     else { *(f32x4*)(xout + off + bj * HALF) = x1[0]; *(f32x4*)(xout + off + bj * HALF + 4) = x1[1]; } }
;                 if (!last) { s2 += shx(s2, 16); s2 += shx(s2, 32); if (fq == 0) P[r * 4 + wc] = s2; }
.LBB0_682:
	v_mul_f32_e32 v93, v93, v93
	v_mul_f32_e32 v89, v89, v89
	v_fmac_f32_e32 v93, v92, v92
	v_mul_f32_e32 v92, v95, v95
	v_fmac_f32_e32 v89, v88, v88
	v_mul_f32_e32 v88, v91, v91
	v_mul_f32_e32 v85, v85, v85
	v_mul_f32_e32 v81, v81, v81
	v_fmac_f32_e32 v92, v94, v94
	v_fmac_f32_e32 v88, v90, v90
	v_fmac_f32_e32 v85, v84, v84
	v_mul_f32_e32 v84, v87, v87
	v_fmac_f32_e32 v81, v80, v80
	v_mul_f32_e32 v80, v83, v83
	v_add_f32_e32 v92, v93, v92
	v_add_f32_e32 v88, v89, v88
	v_fmac_f32_e32 v84, v86, v86
	v_fmac_f32_e32 v80, v82, v82
	v_add_f32_e32 v88, v92, v88
	v_add_f32_e32 v84, v85, v84
	v_add_f32_e32 v80, v81, v80
	v_mbcnt_lo_u32_b32 v81, -1, 0
	v_mbcnt_hi_u32_b32 v81, -1, v81
	v_add_f32_e32 v84, v84, v88
	v_lshlrev_b32_e32 v81, 2, v81
	v_add_f32_e32 v80, v80, v84
	v_xor_b32_e32 v81, 64, v81
	v_mov_b32_e32 v81, v80
	s_nop 1
	v_permlane16_swap_b32_e32 v80, v81
	s_waitcnt lgkmcnt(0)
	v_add_f32_e32 v80, v80, v81
	v_mbcnt_lo_u32_b32 v81, -1, 0
	v_mbcnt_hi_u32_b32 v81, -1, v81
	s_nop 0
	v_lshlrev_b32_e32 v81, 2, v81
	v_xor_b32_e32 v81, 0x80, v81
	v_mov_b32_e32 v81, v80
	s_nop 1
	v_permlane32_swap_b32_e32 v80, v81
	s_and_saveexec_b64 s[38:39], s[6:7]
	s_cbranch_execz .LBB0_684
	v_lshl_add_u32 v82, v102, 4, s82
	s_waitcnt lgkmcnt(0)
	v_add_f32_e32 v80, v80, v81
	ds_write_b32 v82, v80

;     __device__ __forceinline__ void operator()(f32x4 (&acc)[2][2][4][2], const Unit& u, int wr, int wc, int fr_, int fq_) const {
;     ...
;                     for (int n = 0; n < 2; ++n) { x1[n] = xo[n] + gv[bj][n] * acc[ai][bj][m][n] * nh;
;                         s2 += (x1[n][0] * x1[n][0] + x1[n][1] * x1[n][1]) + (x1[n][2] * x1[n][2] + x1[n][3] * x1[n][3]); }
;                     if (!last) store8(xb + off + bj * HALF, x1[0], x1[1]);
;                     else { *(f32x4*)(xout + off + bj * HALF) = x1[0]; *(f32x4*)(xout + off + bj * HALF + 4) = x1[1]; } }
;                 if (!last) { s2 += shx(s2, 16); s2 += shx(s2, 32); if (fq == 0) P[r * 4 + wc] = s2; }
.LBB0_694:
	v_mul_f32_e32 v77, v77, v77
	v_mul_f32_e32 v73, v73, v73
	v_fmac_f32_e32 v77, v76, v76
	v_mul_f32_e32 v76, v79, v79
	v_fmac_f32_e32 v73, v72, v72
	v_mul_f32_e32 v72, v75, v75
	v_mul_f32_e32 v69, v69, v69
	v_mul_f32_e32 v65, v65, v65
	v_fmac_f32_e32 v76, v78, v78
	v_fmac_f32_e32 v72, v74, v74
	v_fmac_f32_e32 v69, v68, v68
	v_mul_f32_e32 v68, v71, v71
	v_fmac_f32_e32 v65, v64, v64
	v_mul_f32_e32 v64, v67, v67
	v_add_f32_e32 v76, v77, v76
	v_add_f32_e32 v72, v73, v72
	v_fmac_f32_e32 v68, v70, v70
	v_fmac_f32_e32 v64, v66, v66
	v_add_f32_e32 v72, v76, v72
	v_add_f32_e32 v68, v69, v68
	v_add_f32_e32 v64, v65, v64
	v_mbcnt_lo_u32_b32 v65, -1, 0
	v_mbcnt_hi_u32_b32 v65, -1, v65
	v_add_f32_e32 v68, v68, v72
	v_lshlrev_b32_e32 v65, 2, v65
	v_add_f32_e32 v64, v64, v68
	v_xor_b32_e32 v65, 64, v65
	v_mov_b32_e32 v65, v64
	s_nop 1
	v_permlane16_swap_b32_e32 v64, v65
	s_waitcnt lgkmcnt(0)
	v_add_f32_e32 v64, v64, v65
	v_mbcnt_lo_u32_b32 v65, -1, 0
	v_mbcnt_hi_u32_b32 v65, -1, v65
	s_nop 0
	v_lshlrev_b32_e32 v65, 2, v65
	v_xor_b32_e32 v65, 0x80, v65
	v_mov_b32_e32 v65, v64
	s_nop 1
	v_permlane32_swap_b32_e32 v64, v65
	s_and_saveexec_b64 s[38:39], s[6:7]
	s_cbranch_execz .LBB0_696
	v_lshl_add_u32 v66, v86, 4, s82
	s_waitcnt lgkmcnt(0)
	v_add_f32_e32 v64, v64, v65
	ds_write_b32 v66, v64

;     __device__ __forceinline__ void operator()(f32x4 (&acc)[2][2][4][2], const Unit& u, int wr, int wc, int fr_, int fq_) const {
;     ...
;                     for (int n = 0; n < 2; ++n) { x1[n] = xo[n] + gv[bj][n] * acc[ai][bj][m][n] * nh;
;                         s2 += (x1[n][0] * x1[n][0] + x1[n][1] * x1[n][1]) + (x1[n][2] * x1[n][2] + x1[n][3] * x1[n][3]); }
;                     if (!last) store8(xb + off + bj * HALF, x1[0], x1[1]);
;                     else { *(f32x4*)(xout + off + bj * HALF) = x1[0]; *(f32x4*)(xout + off + bj * HALF + 4) = x1[1]; } }
;                 if (!last) { s2 += shx(s2, 16); s2 += shx(s2, 32); if (fq == 0) P[r * 4 + wc] = s2; }
.LBB0_706:
	v_mul_f32_e32 v61, v61, v61
	v_mul_f32_e32 v57, v57, v57
	v_fmac_f32_e32 v61, v60, v60
	v_mul_f32_e32 v60, v63, v63
	v_fmac_f32_e32 v57, v56, v56
	v_mul_f32_e32 v56, v59, v59
	v_mul_f32_e32 v53, v53, v53
	v_mul_f32_e32 v49, v49, v49
	v_fmac_f32_e32 v60, v62, v62
	v_fmac_f32_e32 v56, v58, v58
	v_fmac_f32_e32 v53, v52, v52
	v_mul_f32_e32 v52, v55, v55
	v_fmac_f32_e32 v49, v48, v48
	v_mul_f32_e32 v48, v51, v51
	v_add_f32_e32 v60, v61, v60
	v_add_f32_e32 v56, v57, v56
	v_fmac_f32_e32 v52, v54, v54
	v_fmac_f32_e32 v48, v50, v50
	v_add_f32_e32 v56, v60, v56
	v_add_f32_e32 v52, v53, v52
	v_add_f32_e32 v48, v49, v48
	v_mbcnt_lo_u32_b32 v49, -1, 0
	v_mbcnt_hi_u32_b32 v49, -1, v49
	v_add_f32_e32 v52, v52, v56
	v_lshlrev_b32_e32 v49, 2, v49
	v_add_f32_e32 v48, v48, v52
	v_xor_b32_e32 v49, 64, v49
	v_mov_b32_e32 v49, v48
	s_nop 1
	v_permlane16_swap_b32_e32 v48, v49
	s_waitcnt lgkmcnt(0)
	v_add_f32_e32 v48, v48, v49
	v_mbcnt_lo_u32_b32 v49, -1, 0
	v_mbcnt_hi_u32_b32 v49, -1, v49
	s_nop 0
	v_lshlrev_b32_e32 v49, 2, v49
	v_xor_b32_e32 v49, 0x80, v49
	v_mov_b32_e32 v49, v48
	s_nop 1
	v_permlane32_swap_b32_e32 v48, v49
	s_and_saveexec_b64 s[38:39], s[6:7]
	s_cbranch_execz .LBB0_708
	v_lshl_add_u32 v50, v70, 4, s82
	s_waitcnt lgkmcnt(0)
	v_add_f32_e32 v48, v48, v49
	ds_write_b32 v50, v48

;     __device__ __forceinline__ void operator()(f32x4 (&acc)[2][2][4][2], const Unit& u, int wr, int wc, int fr_, int fq_) const {
;     ...
;                     for (int n = 0; n < 2; ++n) { x1[n] = xo[n] + gv[bj][n] * acc[ai][bj][m][n] * nh;
;                         s2 += (x1[n][0] * x1[n][0] + x1[n][1] * x1[n][1]) + (x1[n][2] * x1[n][2] + x1[n][3] * x1[n][3]); }
;                     if (!last) store8(xb + off + bj * HALF, x1[0], x1[1]);
;                     else { *(f32x4*)(xout + off + bj * HALF) = x1[0]; *(f32x4*)(xout + off + bj * HALF + 4) = x1[1]; } }
;                 if (!last) { s2 += shx(s2, 16); s2 += shx(s2, 32); if (fq == 0) P[r * 4 + wc] = s2; }
.LBB0_718:
	v_mul_f32_e32 v45, v45, v45
	v_mul_f32_e32 v41, v41, v41
	v_fmac_f32_e32 v45, v44, v44
	v_mul_f32_e32 v44, v47, v47
	v_fmac_f32_e32 v41, v40, v40
	v_mul_f32_e32 v40, v43, v43
	v_mul_f32_e32 v37, v37, v37
	v_mul_f32_e32 v33, v33, v33
	v_fmac_f32_e32 v44, v46, v46
	v_fmac_f32_e32 v40, v42, v42
	v_fmac_f32_e32 v37, v36, v36
	v_mul_f32_e32 v36, v39, v39
	v_fmac_f32_e32 v33, v32, v32
	v_mul_f32_e32 v32, v35, v35
	v_add_f32_e32 v44, v45, v44
	v_add_f32_e32 v40, v41, v40
	v_fmac_f32_e32 v36, v38, v38
	v_fmac_f32_e32 v32, v34, v34
	v_add_f32_e32 v40, v44, v40
	v_add_f32_e32 v36, v37, v36
	v_add_f32_e32 v32, v33, v32
	v_mbcnt_lo_u32_b32 v33, -1, 0
	v_mbcnt_hi_u32_b32 v33, -1, v33
	v_add_f32_e32 v36, v36, v40
	v_lshlrev_b32_e32 v33, 2, v33
	v_add_f32_e32 v32, v32, v36
	v_xor_b32_e32 v33, 64, v33
	v_mov_b32_e32 v33, v32
	s_nop 1
	v_permlane16_swap_b32_e32 v32, v33
	s_waitcnt lgkmcnt(0)
	v_add_f32_e32 v32, v32, v33
	v_mbcnt_lo_u32_b32 v33, -1, 0
	v_mbcnt_hi_u32_b32 v33, -1, v33
	s_nop 0
	v_lshlrev_b32_e32 v33, 2, v33
	v_xor_b32_e32 v33, 0x80, v33
	v_mov_b32_e32 v33, v32
	s_nop 1
	v_permlane32_swap_b32_e32 v32, v33
	s_and_saveexec_b64 s[38:39], s[6:7]
	s_cbranch_execz .LBB0_720
	v_lshl_add_u32 v34, v54, 4, s82
	s_waitcnt lgkmcnt(0)
	v_add_f32_e32 v32, v32, v33
	ds_write_b32 v34, v32

;     __device__ __forceinline__ void operator()(f32x4 (&acc)[2][2][4][2], const Unit& u, int wr, int wc, int fr_, int fq_) const {
;     ...
;                     for (int n = 0; n < 2; ++n) { x1[n] = xo[n] + gv[bj][n] * acc[ai][bj][m][n] * nh;
;                         s2 += (x1[n][0] * x1[n][0] + x1[n][1] * x1[n][1]) + (x1[n][2] * x1[n][2] + x1[n][3] * x1[n][3]); }
;                     if (!last) store8(xb + off + bj * HALF, x1[0], x1[1]);
;                     else { *(f32x4*)(xout + off + bj * HALF) = x1[0]; *(f32x4*)(xout + off + bj * HALF + 4) = x1[1]; } }
;                 if (!last) { s2 += shx(s2, 16); s2 += shx(s2, 32); if (fq == 0) P[r * 4 + wc] = s2; }
.LBB0_730:
	v_mul_f32_e32 v29, v29, v29
	v_mul_f32_e32 v25, v25, v25
	v_fmac_f32_e32 v29, v28, v28
	v_mul_f32_e32 v28, v31, v31
	v_fmac_f32_e32 v25, v24, v24
	v_mul_f32_e32 v24, v27, v27
	v_mul_f32_e32 v21, v21, v21
	v_mul_f32_e32 v17, v17, v17
	v_fmac_f32_e32 v28, v30, v30
	v_fmac_f32_e32 v24, v26, v26
	v_fmac_f32_e32 v21, v20, v20
	v_mul_f32_e32 v20, v23, v23
	v_fmac_f32_e32 v17, v16, v16
	v_mul_f32_e32 v16, v19, v19
	v_add_f32_e32 v28, v29, v28
	v_add_f32_e32 v24, v25, v24
	v_fmac_f32_e32 v20, v22, v22
	v_fmac_f32_e32 v16, v18, v18
	v_add_f32_e32 v24, v28, v24
	v_add_f32_e32 v20, v21, v20
	v_add_f32_e32 v16, v17, v16
	v_mbcnt_lo_u32_b32 v17, -1, 0
	v_mbcnt_hi_u32_b32 v17, -1, v17
	v_add_f32_e32 v20, v20, v24
	v_lshlrev_b32_e32 v17, 2, v17
	v_add_f32_e32 v16, v16, v20
	v_xor_b32_e32 v17, 64, v17
	v_mov_b32_e32 v17, v16
	s_nop 1
	v_permlane16_swap_b32_e32 v16, v17
	s_waitcnt lgkmcnt(0)
	v_add_f32_e32 v16, v16, v17
	v_mbcnt_lo_u32_b32 v17, -1, 0
	v_mbcnt_hi_u32_b32 v17, -1, v17
	s_nop 0
	v_lshlrev_b32_e32 v17, 2, v17
	v_xor_b32_e32 v17, 0x80, v17
	v_mov_b32_e32 v17, v16
	s_nop 1
	v_permlane32_swap_b32_e32 v16, v17
	s_and_saveexec_b64 s[38:39], s[6:7]
	s_cbranch_execz .LBB0_732
	v_lshl_add_u32 v18, v38, 4, s82
	s_waitcnt lgkmcnt(0)
	v_add_f32_e32 v16, v16, v17
	ds_write_b32 v18, v16

;     __device__ __forceinline__ void operator()(f32x4 (&acc)[2][2][4][2], const Unit& u, int wr, int wc, int fr_, int fq_) const {
;     ...
;                     for (int n = 0; n < 2; ++n) { x1[n] = xo[n] + gv[bj][n] * acc[ai][bj][m][n] * nh;
;                         s2 += (x1[n][0] * x1[n][0] + x1[n][1] * x1[n][1]) + (x1[n][2] * x1[n][2] + x1[n][3] * x1[n][3]); }
;                     if (!last) store8(xb + off + bj * HALF, x1[0], x1[1]);
;                     else { *(f32x4*)(xout + off + bj * HALF) = x1[0]; *(f32x4*)(xout + off + bj * HALF + 4) = x1[1]; } }
;                 if (!last) { s2 += shx(s2, 16); s2 += shx(s2, 32); if (fq == 0) P[r * 4 + wc] = s2; }
.LBB0_742:
	v_mul_f32_e32 v13, v13, v13
	v_mul_f32_e32 v9, v9, v9
	v_fmac_f32_e32 v13, v12, v12
	v_mul_f32_e32 v12, v15, v15
	v_fmac_f32_e32 v9, v8, v8
	v_mul_f32_e32 v8, v11, v11
	v_mul_f32_e32 v5, v5, v5
	v_mul_f32_e32 v1, v1, v1
	v_fmac_f32_e32 v12, v14, v14
	v_fmac_f32_e32 v8, v10, v10
	v_fmac_f32_e32 v5, v4, v4
	v_mul_f32_e32 v4, v7, v7
	v_fmac_f32_e32 v1, v0, v0
	v_mul_f32_e32 v0, v3, v3
	v_add_f32_e32 v12, v13, v12
	v_add_f32_e32 v8, v9, v8
	v_fmac_f32_e32 v4, v6, v6
	v_fmac_f32_e32 v0, v2, v2
	v_add_f32_e32 v8, v12, v8
	v_add_f32_e32 v4, v5, v4
	v_add_f32_e32 v0, v1, v0
	v_mbcnt_lo_u32_b32 v1, -1, 0
	v_mbcnt_hi_u32_b32 v1, -1, v1
	v_add_f32_e32 v4, v4, v8
	v_lshlrev_b32_e32 v1, 2, v1
	v_add_f32_e32 v0, v0, v4
	v_xor_b32_e32 v1, 64, v1
	v_mov_b32_e32 v1, v0
	s_nop 1
	v_permlane16_swap_b32_e32 v0, v1
	s_waitcnt lgkmcnt(0)
	v_add_f32_e32 v0, v0, v1
	v_mbcnt_lo_u32_b32 v1, -1, 0
	v_mbcnt_hi_u32_b32 v1, -1, v1
	s_nop 0
	v_lshlrev_b32_e32 v1, 2, v1
	v_xor_b32_e32 v1, 0x80, v1
	v_mov_b32_e32 v1, v0
	s_nop 1
	v_permlane32_swap_b32_e32 v0, v1
	s_and_saveexec_b64 s[38:39], s[6:7]
	s_cbranch_execz .LBB0_744
	v_lshl_add_u32 v2, v22, 4, s82
	s_waitcnt lgkmcnt(0)
	v_add_f32_e32 v0, v0, v1
	ds_write_b32 v2, v0
